# v54 + XCD leaders post their cross-XCD arrival and poll the arrival counter directly (no returning atomic, no separate release word)
# baseline (speedup 1.0000x reference)
; __device__ __forceinline__ unsigned xb_ld(unsigned* p)              { return __hip_atomic_load(p, __ATOMIC_RELAXED, __HIP_MEMORY_SCOPE_AGENT); }
; __device__ __forceinline__ unsigned xb_add(unsigned* p, unsigned v) { return __hip_atomic_fetch_add(p, v, __ATOMIC_RELAXED, __HIP_MEMORY_SCOPE_AGENT); }
; #define XB_SPIN(cond, bar) do { unsigned _sp = 0; while (cond) { __builtin_amdgcn_s_sleep(1); \
;     if ((++_sp & 255u) == 0u) { if (xb_ld(&(bar)[XB_TMO])) break; if (_sp > XB_SPIN_CAP) { atomicAdd(&(bar)[XB_TMO], 1u); break; } } } } while (0)
; __device__ __forceinline__ void xcd_barrier(const XcdBarrier& b) {
;     ...
;         const unsigned old = xb_add(&bar[XB_XSUB(b.x)], 1u);
;         const unsigned gen = old / nloc;
;         if (old + 1u == (gen + 1u) * nloc) {
;             __builtin_amdgcn_fence(__ATOMIC_RELEASE, "agent");
;             asm volatile("s_waitcnt vmcnt(0)" ::: "memory");
;             const unsigned og = xb_add(&bar[XB_TOP], 1u);
;             const unsigned tg = og / nx;
;             if (og + 1u == (tg + 1u) * nx) xb_add(&bar[XB_TOPGEN], 1u);
;             else XB_SPIN(xb_ld(&bar[XB_TOPGEN]) == tg, bar);
;             __builtin_amdgcn_fence(__ATOMIC_ACQUIRE, "agent");
;             xb_add(&bar[XB_XGEN(b.x)], 1u);
;             asm volatile("s_waitcnt vmcnt(0)" ::: "memory");
.LBB0_864:
	s_mov_b64 s[8:9], exec
	v_mad_u32_u24 v5, v1, v0, v0
	buffer_wbl2 sc1
	s_waitcnt lgkmcnt(0)
	s_waitcnt vmcnt(0)
	v_readlane_b32 s2, v254, 4
	v_readlane_b32 s3, v254, 5
	v_mov_b32_e32 v2, 1
	s_mov_b32 s10, 0
	s_nop 4
	global_atomic_add v113, v2, s[2:3]
.Lxb_poll:
	global_load_dword v0, v113, s[2:3] sc1
	s_waitcnt vmcnt(0)
	v_sub_u32_e32 v0, v0, v5
	v_cmp_gt_i32_e32 vcc, 0, v0
	s_cbranch_vccz .Lxb_done
	s_sleep 1
	s_add_i32 s10, s10, 1
	s_cmp_lt_u32 s10, 0x40000
	s_cbranch_scc1 .Lxb_poll
.Lxb_done:
	s_getpc_b64 s[98:99]
